# MoBA stagger roles swapped: waves 0-3 defer PV by one tile, waves 4-7 run S->softmax||PV
# speedup vs baseline: 1.0018x; 1.0018x over previous
; #define MOBA_LOAD(jj, kk) do { const size_t r_ = (rowb + (jj) * 256 + (kk) * 64 + lrow) * D_ + h * 128 + lc * 16; rk0 = *(const u32x4*)(MBK + r_); rk1 = *(const u32x4*)(MBK + r_ + 8); rv0 = *(const u32x4*)(MBV + r_); rv1 = *(const u32x4*)(MBV + r_ + 8); } while (0)
; __device__ __forceinline__ void phase_moba_mfma(const Params& p, LAS unsigned char* lds, unsigned lds_base) {
;     ...
;         while (j >= 0) {
;             int nj = j, nkt = kt + 1;
;     ...
;             if (nj >= 0) MOBA_LOAD(nj, nkt);
;             const bool own = (j == qb);
;             bool need;
;             if (own) need = (kt * 64 <= 32 * wave + 31); else need = (__ballot((sel >> j) & 1u) != 0ull);
;             if (need) {
.LBB0_747:
	s_cmp_ge_u32 s18, 0x80
	s_cbranch_scc1 .Lmoba_bodyA
	s_bitcmp0_b32 s2, 0
	s_cbranch_scc1 .Lmoba_bodyB
	s_add_i32 s0, s100, 3
	s_and_b32 s0, s0, 3
	s_mov_b32 s45, 0
	s_branch .Lmoba_pvblk
